# both layer-1 bias vectors (w_in and gate/up) computed in the idle tail of the layer-0 w_out phase, wave index rotated to cap at three groups per wave
# baseline (speedup 1.0000x reference)
.LBB0_612:
	s_mov_b32 s0, 0
	v_readlane_b32 s94, v254, 6
	s_lshl_b32 s95, s94, 3
	s_sub_i32 s95, s90, s95
	s_sub_i32 s96, s70, s94
	s_mov_b32 s97, s95
	s_cmp_lg_u32 s94, 0x60
	s_cbranch_scc1 .Lb1_norot
	s_cmp_lg_u32 s70, 0x100
	s_cbranch_scc1 .Lb1_norot
	s_add_i32 s97, s95, 0xffffff80
	s_add_i32 s98, s95, 0x480
	s_cmp_lt_i32 s97, 0
	s_cselect_b32 s97, s98, s97
	s_add_i32 s98, s95, 0x300
	s_add_i32 s95, s95, 0xfffffe00
	s_cmp_lt_i32 s95, 0
	s_cselect_b32 s95, s98, s95
.Lb1_norot:
	s_load_dwordx2 s[8:9], s[82:83], 0xb0
	s_cmp_lt_i32 s93, s94
	s_cbranch_scc1 .Lb1_done
	v_mbcnt_lo_u32_b32 v0, -1, s0
	v_mbcnt_hi_u32_b32 v130, -1, v0
	s_lshl_b32 s10, s95, 2
	s_cmpk_gt_i32 s95, 0x2ff
	v_lshlrev_b32_e32 v64, 4, v130
	v_lshlrev_b32_e32 v131, 2, v130
	v_cmp_eq_u32_e64 s[6:7], 0, v130
	s_cbranch_scc1 .LBB0_917
	v_ashrrev_i32_e32 v65, 31, v64
	s_waitcnt lgkmcnt(0)
	v_lshl_add_u64 v[0:1], v[64:65], 2, s[8:9]
	s_mov_b64 s[0:1], 0x2e000
	v_lshl_add_u64 v[66:67], v[0:1], 0, s[0:1]
	s_mov_b64 s[0:1], 0x34000
	v_lshl_add_u64 v[68:69], v[0:1], 0, s[0:1]
	s_mov_b64 s[0:1], 0x3a000
	v_lshl_add_u64 v[70:71], v[0:1], 0, s[0:1]
	s_mov_b64 s[0:1], 0x40000
	s_lshl_b32 s4, s96, 5
	v_lshl_add_u64 v[72:73], v[0:1], 0, s[0:1]
	s_mov_b64 s[0:1], 0x46000
	s_ashr_i32 s11, s10, 31
	v_lshl_add_u64 v[74:75], v[0:1], 0, s[0:1]
	s_lshl_b64 s[0:1], s[10:11], 11
	s_ashr_i32 s5, s4, 31
	v_xor_b32_e32 v132, 0x80, v131
	v_lshl_add_u64 v[76:77], v[64:65], 1, s[0:1]
	s_lshl_b64 s[12:13], s[4:5], 11
	s_lshl_b64 s[14:15], s[10:11], 2
	s_lshl_b64 s[16:17], s[4:5], 2
	s_mov_b64 s[18:19], 0x1700000
	s_mov_b64 s[20:21], 0x1700800
	s_mov_b64 s[22:23], 0x1701000
	s_mov_b32 s0, 0x1701000
	s_mov_b64 s[24:25], 0x1701800
	v_mov_b32_e32 v65, 0xcb000
	v_mov_b32_e32 v133, 0xce000
	v_mov_b32_e32 v134, 0xd1000
	v_mov_b32_e32 v135, 0xd4000
	v_mov_b32_e32 v136, 0xd7000
	s_mov_b32 s1, s10
	s_branch .LBB0_915

.LBB0_917:
	s_lshl_b32 s10, s97, 2
	s_cmpk_gt_i32 s97, 0x57f
	s_cbranch_scc1 .Lb1_done
	v_ashrrev_i32_e32 v65, 31, v64
	s_waitcnt lgkmcnt(0)
	v_lshl_add_u64 v[0:1], v[64:65], 2, s[8:9]
	s_mov_b64 s[0:1], 0x31000
	v_lshl_add_u64 v[66:67], v[0:1], 0, s[0:1]
	s_mov_b64 s[0:1], 0x37000
	v_lshl_add_u64 v[68:69], v[0:1], 0, s[0:1]
	s_mov_b64 s[0:1], 0x3d000
	v_lshl_add_u64 v[70:71], v[0:1], 0, s[0:1]
	s_mov_b64 s[0:1], 0x43000
	s_lshl_b32 s4, s96, 5
	v_lshl_add_u64 v[72:73], v[0:1], 0, s[0:1]
	s_mov_b64 s[0:1], 0x49000
	s_ashr_i32 s11, s10, 31
	v_lshl_add_u64 v[74:75], v[0:1], 0, s[0:1]
	s_lshl_b64 s[0:1], s[10:11], 11
	s_ashr_i32 s5, s4, 31
	v_xor_b32_e32 v128, 0x80, v131
	v_cmp_eq_u32_e64 s[6:7], 0, v130
	v_lshl_add_u64 v[64:65], v[64:65], 1, s[0:1]
	s_lshl_b64 s[12:13], s[4:5], 11
	s_lshl_b64 s[14:15], s[10:11], 2
	s_lshl_b64 s[16:17], s[4:5], 2
	s_mov_b64 s[18:19], 0x1f00000
	s_mov_b64 s[20:21], 0x1f00800
	s_mov_b64 s[22:23], 0x1f01000
	s_mov_b32 s0, 0x1f01000
	s_mov_b64 s[24:25], 0x1f01800
	v_mov_b32_e32 v129, 0xda000
	v_mov_b32_e32 v130, 0xe0000
	v_mov_b32_e32 v131, 0xe5000
	v_mov_b32_e32 v132, 0xeb000
	v_mov_b32_e32 v133, 0xf0000
	s_branch .LBB0_920

.Lb1_done:
	s_mov_b32 s0, 0
	s_and_b64 vcc, exec, s[76:77]
	s_waitcnt lgkmcnt(0)
	s_mov_b64 s[8:9], 0
	s_cbranch_vccnz .LBB0_614
	v_mbcnt_lo_u32_b32 v0, -1, s0
	v_mbcnt_hi_u32_b32 v0, -1, v0
	v_cmp_eq_u32_e32 vcc, 0, v0
	s_and_b64 s[8:9], vcc, exec
.LBB0_614:
	s_load_dwordx2 s[6:7], s[82:83], 0xb0
	s_getreg_b32 s0, hwreg(HW_REG_XCC_ID, 0, 4)
	s_waitcnt vmcnt(0)
	s_waitcnt vmcnt(0) lgkmcnt(0)
	s_barrier
	s_and_saveexec_b64 s[4:5], s[8:9]
	s_cbranch_execz .LBB0_666
	s_add_i32 s1, 0, 0x25000
	v_mov_b32_e32 v0, s1
	s_waitcnt vmcnt(0) expcnt(0) lgkmcnt(0)
	ds_read_b32 v2, v0
	s_add_i32 s1, 0, 0x25004
	v_mov_b32_e32 v0, s1
	ds_read_b32 v0, v0
	s_and_b32 s0, s0, 15
	s_waitcnt lgkmcnt(1)
	v_cmp_ne_u32_e32 vcc, 0, v2
	s_cbranch_vccnz .LBB0_630
	s_add_u32 s8, s6, 0x1000
	s_addc_u32 s9, s7, 0
	s_add_u32 s10, s6, 0x1100
	s_addc_u32 s11, s7, 0
	s_add_u32 s12, s6, 0x1200
	s_addc_u32 s13, s7, 0
	s_mul_i32 s1, s71, s72
	s_add_u32 s14, s6, 0x1300
	s_mul_i32 s1, s1, s70
	s_addc_u32 s15, s7, 0
	s_mov_b32 s2, 1
	v_mov_b32_e32 v16, 0
	s_branch .LBB0_618

.LBB0_911:
.LBB0_922:
	s_mov_b32 s0, 0
	s_and_b64 vcc, exec, s[76:77]
	s_waitcnt lgkmcnt(0)
	s_mov_b64 s[8:9], 0
	s_cbranch_vccnz .LBB0_924
	v_mbcnt_lo_u32_b32 v0, -1, s0
	v_mbcnt_hi_u32_b32 v0, -1, v0
	v_cmp_eq_u32_e32 vcc, 0, v0
	s_and_b64 s[8:9], vcc, exec
